# A/B: all s_setprio flips removed from the three GEMM K-loops
# speedup vs baseline: 1.0069x; 1.0069x over previous
.LBB0_232:
	s_add_u32 s0, s84, 0xfffc0080
	s_addc_u32 s86, s85, -1
	s_add_i32 s96, 0, 0x10000
	s_cmp_eq_u32 s90, 12
	s_cselect_b32 s89, s66, s86
	s_cselect_b32 s88, s67, s0
	s_cselect_b32 s87, s68, s77
	s_cselect_b32 s86, s69, s75
	s_add_i32 s0, 0, 0x14000
	v_add_u32_e32 v160, s96, v145
	v_add_u32_e32 v176, s0, v145
	ds_read_b128 v[140:143], v160
	ds_read_b128 v[152:155], v160 offset:1024
	ds_read_b128 v[156:159], v160 offset:2048
	ds_read_b128 v[160:163], v160 offset:3072
	ds_read_b128 v[164:167], v176
	ds_read_b128 v[168:171], v176 offset:1024
	ds_read_b128 v[172:175], v176 offset:2048
	ds_read_b128 v[176:179], v176 offset:3072
	v_lshl_add_u64 v[180:181], s[84:85], 0, v[136:137]
	s_add_i32 m0, s22, 0xc000
	ds_read_b128 v[188:191], v151
	ds_read_b128 v[220:223], v151 offset:1024
	ds_read_b128 v[224:227], v151 offset:2048
	ds_read_b128 v[228:231], v151 offset:3072
	ds_read_b128 v[232:235], v151 offset:4096
	ds_read_b128 v[236:239], v151 offset:5120
	ds_read_b128 v[240:243], v151 offset:6144
	ds_read_b128 v[244:247], v151 offset:7168
	global_load_lds_dwordx4 v[180:181], off
	v_lshl_add_u64 v[180:181], s[84:85], 0, v[138:139]
	s_add_i32 m0, s22, 0xe000
	s_nop 0
	global_load_lds_dwordx4 v[180:181], off
	s_waitcnt vmcnt(8)
	s_waitcnt lgkmcnt(0)
	s_barrier
	s_waitcnt lgkmcnt(0)
	v_mfma_f32_16x16x32_bf16 v[128:131], v[140:143], v[188:191], v[128:131]
	v_mfma_f32_16x16x32_bf16 v[124:127], v[156:159], v[188:191], v[124:127]
	v_mfma_f32_16x16x32_bf16 v[112:115], v[140:143], v[224:227], v[112:115]
	v_mfma_f32_16x16x32_bf16 v[108:111], v[156:159], v[224:227], v[108:111]
	v_mfma_f32_16x16x32_bf16 v[92:95], v[140:143], v[232:235], v[92:95]
	v_mfma_f32_16x16x32_bf16 v[88:91], v[156:159], v[232:235], v[88:91]
	v_mfma_f32_16x16x32_bf16 v[76:79], v[140:143], v[240:243], v[76:79]
	v_mfma_f32_16x16x32_bf16 v[72:75], v[156:159], v[240:243], v[72:75]
	v_mfma_f32_16x16x32_bf16 v[128:131], v[152:155], v[220:223], v[128:131]
	v_mfma_f32_16x16x32_bf16 v[124:127], v[160:163], v[220:223], v[124:127]
	v_mfma_f32_16x16x32_bf16 v[112:115], v[152:155], v[228:231], v[112:115]
	v_mfma_f32_16x16x32_bf16 v[108:111], v[160:163], v[228:231], v[108:111]
	v_mfma_f32_16x16x32_bf16 v[92:95], v[152:155], v[236:239], v[92:95]
	v_mfma_f32_16x16x32_bf16 v[88:91], v[160:163], v[236:239], v[88:91]
	v_mfma_f32_16x16x32_bf16 v[76:79], v[152:155], v[244:247], v[76:79]
	v_mfma_f32_16x16x32_bf16 v[72:75], v[160:163], v[244:247], v[72:75]
	v_mfma_f32_16x16x32_bf16 v[120:123], v[164:167], v[188:191], v[120:123]
	v_mfma_f32_16x16x32_bf16 v[116:119], v[172:175], v[188:191], v[116:119]
	v_mfma_f32_16x16x32_bf16 v[104:107], v[164:167], v[224:227], v[104:107]
	v_mfma_f32_16x16x32_bf16 v[100:103], v[172:175], v[224:227], v[100:103]
	v_mfma_f32_16x16x32_bf16 v[84:87], v[164:167], v[232:235], v[84:87]
	v_mfma_f32_16x16x32_bf16 v[80:83], v[172:175], v[232:235], v[80:83]
	v_mfma_f32_16x16x32_bf16 v[68:71], v[164:167], v[240:243], v[68:71]
	v_mfma_f32_16x16x32_bf16 v[64:67], v[172:175], v[240:243], v[64:67]
	v_mfma_f32_16x16x32_bf16 v[120:123], v[168:171], v[220:223], v[120:123]
	v_mfma_f32_16x16x32_bf16 v[116:119], v[176:179], v[220:223], v[116:119]
	v_mfma_f32_16x16x32_bf16 v[104:107], v[168:171], v[228:231], v[104:107]
	v_mfma_f32_16x16x32_bf16 v[100:103], v[176:179], v[228:231], v[100:103]
	v_mfma_f32_16x16x32_bf16 v[84:87], v[168:171], v[236:239], v[84:87]
	v_mfma_f32_16x16x32_bf16 v[80:83], v[176:179], v[236:239], v[80:83]
	v_mfma_f32_16x16x32_bf16 v[68:71], v[168:171], v[244:247], v[68:71]
	v_mfma_f32_16x16x32_bf16 v[64:67], v[176:179], v[244:247], v[64:67]
	s_barrier
	s_add_i32 s96, s96, s1
	v_lshl_add_u64 v[180:181], s[86:87], 0, v[98:99]
	s_mov_b32 m0, s96
	ds_read_b128 v[188:191], v151 offset:16384
	ds_read_b128 v[220:223], v151 offset:17408
	ds_read_b128 v[224:227], v151 offset:18432
	ds_read_b128 v[228:231], v151 offset:19456
	ds_read_b128 v[232:235], v151 offset:20480
	ds_read_b128 v[236:239], v151 offset:21504
	ds_read_b128 v[240:243], v151 offset:22528
	ds_read_b128 v[244:247], v151 offset:23552
	global_load_lds_dwordx4 v[180:181], off
	s_add_i32 m0, s96, 0x2000
	s_add_u32 s96, s86, 0x40000
	v_lshl_add_u64 v[192:193], s[86:87], 0, v[134:135]
	s_addc_u32 s97, s87, 0
	s_add_i32 s0, s0, s1
	global_load_lds_dwordx4 v[192:193], off
	v_lshl_add_u64 v[248:249], s[96:97], 0, v[98:99]
	s_mov_b32 m0, s0
	v_lshl_add_u64 v[250:251], s[88:89], 0, v[132:133]
	global_load_lds_dwordx4 v[248:249], off
	v_lshl_add_u64 v[248:249], s[96:97], 0, v[134:135]
	s_add_i32 m0, s0, 0x2000
	s_nop 0
	global_load_lds_dwordx4 v[248:249], off
	v_lshl_add_u64 v[248:249], s[88:89], 0, v[96:97]
	s_mov_b32 m0, s22
	s_nop 0
	global_load_lds_dwordx4 v[248:249], off
	s_mov_b32 m0, s23
	s_nop 0
	global_load_lds_dwordx4 v[250:251], off
	s_waitcnt vmcnt(8)
	s_waitcnt lgkmcnt(0)
	s_barrier
	s_waitcnt lgkmcnt(0)
	v_mfma_f32_16x16x32_bf16 v[60:63], v[140:143], v[188:191], v[60:63]
	v_mfma_f32_16x16x32_bf16 v[56:59], v[156:159], v[188:191], v[56:59]
	v_mfma_f32_16x16x32_bf16 v[44:47], v[140:143], v[224:227], v[44:47]
	v_mfma_f32_16x16x32_bf16 v[40:43], v[156:159], v[224:227], v[40:43]
	v_mfma_f32_16x16x32_bf16 v[28:31], v[140:143], v[232:235], v[28:31]
	v_mfma_f32_16x16x32_bf16 v[24:27], v[156:159], v[232:235], v[24:27]
	v_mfma_f32_16x16x32_bf16 v[12:15], v[140:143], v[240:243], v[12:15]
	v_mfma_f32_16x16x32_bf16 v[8:11], v[156:159], v[240:243], v[8:11]
	v_mfma_f32_16x16x32_bf16 v[60:63], v[152:155], v[220:223], v[60:63]
	v_mfma_f32_16x16x32_bf16 v[56:59], v[160:163], v[220:223], v[56:59]
	v_mfma_f32_16x16x32_bf16 v[44:47], v[152:155], v[228:231], v[44:47]
	v_mfma_f32_16x16x32_bf16 v[40:43], v[160:163], v[228:231], v[40:43]
	v_mfma_f32_16x16x32_bf16 v[28:31], v[152:155], v[236:239], v[28:31]
	v_mfma_f32_16x16x32_bf16 v[24:27], v[160:163], v[236:239], v[24:27]
	v_mfma_f32_16x16x32_bf16 v[12:15], v[152:155], v[244:247], v[12:15]
	v_mfma_f32_16x16x32_bf16 v[8:11], v[160:163], v[244:247], v[8:11]
	v_mfma_f32_16x16x32_bf16 v[52:55], v[164:167], v[188:191], v[52:55]
	v_mfma_f32_16x16x32_bf16 v[48:51], v[172:175], v[188:191], v[48:51]
	v_mfma_f32_16x16x32_bf16 v[36:39], v[164:167], v[224:227], v[36:39]
	v_mfma_f32_16x16x32_bf16 v[32:35], v[172:175], v[224:227], v[32:35]
	v_mfma_f32_16x16x32_bf16 v[20:23], v[164:167], v[232:235], v[20:23]
	v_mfma_f32_16x16x32_bf16 v[16:19], v[172:175], v[232:235], v[16:19]
	v_mfma_f32_16x16x32_bf16 v[4:7], v[164:167], v[240:243], v[4:7]
	v_mfma_f32_16x16x32_bf16 v[0:3], v[172:175], v[240:243], v[0:3]
	v_mfma_f32_16x16x32_bf16 v[52:55], v[168:171], v[220:223], v[52:55]
	v_mfma_f32_16x16x32_bf16 v[48:51], v[176:179], v[220:223], v[48:51]
	v_mfma_f32_16x16x32_bf16 v[36:39], v[168:171], v[228:231], v[36:39]
	v_mfma_f32_16x16x32_bf16 v[32:35], v[176:179], v[228:231], v[32:35]
	v_mfma_f32_16x16x32_bf16 v[20:23], v[168:171], v[236:239], v[20:23]
	v_mfma_f32_16x16x32_bf16 v[16:19], v[176:179], v[236:239], v[16:19]
	v_mfma_f32_16x16x32_bf16 v[4:7], v[168:171], v[244:247], v[4:7]
	v_mfma_f32_16x16x32_bf16 v[0:3], v[176:179], v[244:247], v[0:3]
	s_barrier
	s_add_i32 s0, 0, 0x18000
	s_add_i32 s96, 0, 0x1c000
	v_add_u32_e32 v160, s0, v145
	v_add_u32_e32 v176, s96, v145
	ds_read_b128 v[140:143], v160
	ds_read_b128 v[152:155], v160 offset:1024
	ds_read_b128 v[156:159], v160 offset:2048
	ds_read_b128 v[160:163], v160 offset:3072
	ds_read_b128 v[164:167], v176
	ds_read_b128 v[168:171], v176 offset:1024
	ds_read_b128 v[172:175], v176 offset:2048
	ds_read_b128 v[176:179], v176 offset:3072
	s_add_u32 s88, s88, 0x40000
	s_addc_u32 s89, s89, 0
	s_mov_b32 m0, s26
	v_lshl_add_u64 v[252:253], s[88:89], 0, v[96:97]
	ds_read_b128 v[188:191], v151 offset:32768
	ds_read_b128 v[220:223], v151 offset:33792
	ds_read_b128 v[224:227], v151 offset:34816
	ds_read_b128 v[228:231], v151 offset:35840
	ds_read_b128 v[232:235], v151 offset:36864
	ds_read_b128 v[236:239], v151 offset:37888
	ds_read_b128 v[240:243], v151 offset:38912
	ds_read_b128 v[244:247], v151 offset:39936
	global_load_lds_dwordx4 v[252:253], off
	v_lshl_add_u64 v[252:253], s[88:89], 0, v[132:133]
	s_mov_b32 m0, s27
	s_nop 0
	global_load_lds_dwordx4 v[252:253], off
	s_waitcnt vmcnt(8)
	s_waitcnt lgkmcnt(0)
	s_barrier
	s_waitcnt lgkmcnt(0)
	v_mfma_f32_16x16x32_bf16 v[128:131], v[140:143], v[188:191], v[128:131]
	v_mfma_f32_16x16x32_bf16 v[124:127], v[156:159], v[188:191], v[124:127]
	v_mfma_f32_16x16x32_bf16 v[112:115], v[140:143], v[224:227], v[112:115]
	v_mfma_f32_16x16x32_bf16 v[108:111], v[156:159], v[224:227], v[108:111]
	v_mfma_f32_16x16x32_bf16 v[92:95], v[140:143], v[232:235], v[92:95]
	v_mfma_f32_16x16x32_bf16 v[88:91], v[156:159], v[232:235], v[88:91]
	v_mfma_f32_16x16x32_bf16 v[76:79], v[140:143], v[240:243], v[76:79]
	v_mfma_f32_16x16x32_bf16 v[72:75], v[156:159], v[240:243], v[72:75]
	v_mfma_f32_16x16x32_bf16 v[128:131], v[152:155], v[220:223], v[128:131]
	v_mfma_f32_16x16x32_bf16 v[124:127], v[160:163], v[220:223], v[124:127]
	v_mfma_f32_16x16x32_bf16 v[112:115], v[152:155], v[228:231], v[112:115]
	v_mfma_f32_16x16x32_bf16 v[108:111], v[160:163], v[228:231], v[108:111]
	v_mfma_f32_16x16x32_bf16 v[92:95], v[152:155], v[236:239], v[92:95]
	v_mfma_f32_16x16x32_bf16 v[88:91], v[160:163], v[236:239], v[88:91]
	v_mfma_f32_16x16x32_bf16 v[76:79], v[152:155], v[244:247], v[76:79]
	v_mfma_f32_16x16x32_bf16 v[72:75], v[160:163], v[244:247], v[72:75]
	v_mfma_f32_16x16x32_bf16 v[120:123], v[164:167], v[188:191], v[120:123]
	v_mfma_f32_16x16x32_bf16 v[116:119], v[172:175], v[188:191], v[116:119]
	v_mfma_f32_16x16x32_bf16 v[104:107], v[164:167], v[224:227], v[104:107]
	v_mfma_f32_16x16x32_bf16 v[100:103], v[172:175], v[224:227], v[100:103]
	v_mfma_f32_16x16x32_bf16 v[84:87], v[164:167], v[232:235], v[84:87]
	v_mfma_f32_16x16x32_bf16 v[80:83], v[172:175], v[232:235], v[80:83]
	v_mfma_f32_16x16x32_bf16 v[68:71], v[164:167], v[240:243], v[68:71]
	v_mfma_f32_16x16x32_bf16 v[64:67], v[172:175], v[240:243], v[64:67]
	v_mfma_f32_16x16x32_bf16 v[120:123], v[168:171], v[220:223], v[120:123]
	v_mfma_f32_16x16x32_bf16 v[116:119], v[176:179], v[220:223], v[116:119]
	v_mfma_f32_16x16x32_bf16 v[104:107], v[168:171], v[228:231], v[104:107]
	v_mfma_f32_16x16x32_bf16 v[100:103], v[176:179], v[228:231], v[100:103]
	v_mfma_f32_16x16x32_bf16 v[84:87], v[168:171], v[236:239], v[84:87]
	v_mfma_f32_16x16x32_bf16 v[80:83], v[176:179], v[236:239], v[80:83]
	v_mfma_f32_16x16x32_bf16 v[68:71], v[168:171], v[244:247], v[68:71]
	v_mfma_f32_16x16x32_bf16 v[64:67], v[176:179], v[244:247], v[64:67]
	s_barrier
	s_add_i32 s0, s0, s1
	v_lshl_add_u64 v[180:181], v[180:181], 0, s[58:59]
	s_mov_b32 m0, s0
	ds_read_b128 v[188:191], v151 offset:49152
	ds_read_b128 v[220:223], v151 offset:50176
	ds_read_b128 v[224:227], v151 offset:51200
	ds_read_b128 v[228:231], v151 offset:52224
	ds_read_b128 v[232:235], v151 offset:53248
	ds_read_b128 v[236:239], v151 offset:54272
	ds_read_b128 v[240:243], v151 offset:55296
	ds_read_b128 v[244:247], v151 offset:56320
	global_load_lds_dwordx4 v[180:181], off
	s_add_i32 m0, s0, 0x2000
	s_add_u32 s86, s86, 0x40080
	v_lshl_add_u64 v[180:181], v[192:193], 0, s[58:59]
	s_addc_u32 s87, s87, 0
	s_add_i32 s0, s96, s1
	global_load_lds_dwordx4 v[180:181], off
	v_lshl_add_u64 v[180:181], s[86:87], 0, v[98:99]
	s_mov_b32 m0, s0
	s_nop 0
	global_load_lds_dwordx4 v[180:181], off
	v_lshl_add_u64 v[180:181], s[86:87], 0, v[134:135]
	s_add_i32 m0, s0, 0x2000
	s_nop 0
	global_load_lds_dwordx4 v[180:181], off
	v_lshl_add_u64 v[180:181], v[248:249], 0, s[58:59]
	s_mov_b32 m0, s42
	s_nop 0
	global_load_lds_dwordx4 v[180:181], off
	v_lshl_add_u64 v[180:181], v[250:251], 0, s[58:59]
	s_mov_b32 m0, s43
	s_nop 0
	global_load_lds_dwordx4 v[180:181], off
	s_waitcnt vmcnt(8)
	s_waitcnt lgkmcnt(0)
	s_barrier
	s_waitcnt lgkmcnt(0)
	v_mfma_f32_16x16x32_bf16 v[60:63], v[140:143], v[188:191], v[60:63]
	v_mfma_f32_16x16x32_bf16 v[56:59], v[156:159], v[188:191], v[56:59]
	v_mfma_f32_16x16x32_bf16 v[44:47], v[140:143], v[224:227], v[44:47]
	v_mfma_f32_16x16x32_bf16 v[40:43], v[156:159], v[224:227], v[40:43]
	v_mfma_f32_16x16x32_bf16 v[28:31], v[140:143], v[232:235], v[28:31]
	v_mfma_f32_16x16x32_bf16 v[24:27], v[156:159], v[232:235], v[24:27]
	v_mfma_f32_16x16x32_bf16 v[12:15], v[140:143], v[240:243], v[12:15]
	v_mfma_f32_16x16x32_bf16 v[8:11], v[156:159], v[240:243], v[8:11]
	v_mfma_f32_16x16x32_bf16 v[60:63], v[152:155], v[220:223], v[60:63]
	v_mfma_f32_16x16x32_bf16 v[56:59], v[160:163], v[220:223], v[56:59]
	v_mfma_f32_16x16x32_bf16 v[44:47], v[152:155], v[228:231], v[44:47]
	v_mfma_f32_16x16x32_bf16 v[40:43], v[160:163], v[228:231], v[40:43]
	v_mfma_f32_16x16x32_bf16 v[28:31], v[152:155], v[236:239], v[28:31]
	v_mfma_f32_16x16x32_bf16 v[24:27], v[160:163], v[236:239], v[24:27]
	v_mfma_f32_16x16x32_bf16 v[12:15], v[152:155], v[244:247], v[12:15]
	v_mfma_f32_16x16x32_bf16 v[8:11], v[160:163], v[244:247], v[8:11]
	v_mfma_f32_16x16x32_bf16 v[52:55], v[164:167], v[188:191], v[52:55]
	v_mfma_f32_16x16x32_bf16 v[48:51], v[172:175], v[188:191], v[48:51]
	v_mfma_f32_16x16x32_bf16 v[36:39], v[164:167], v[224:227], v[36:39]
	v_mfma_f32_16x16x32_bf16 v[32:35], v[172:175], v[224:227], v[32:35]
	v_mfma_f32_16x16x32_bf16 v[20:23], v[164:167], v[232:235], v[20:23]
	v_mfma_f32_16x16x32_bf16 v[16:19], v[172:175], v[232:235], v[16:19]
	v_mfma_f32_16x16x32_bf16 v[4:7], v[164:167], v[240:243], v[4:7]
	v_mfma_f32_16x16x32_bf16 v[0:3], v[172:175], v[240:243], v[0:3]
	v_mfma_f32_16x16x32_bf16 v[52:55], v[168:171], v[220:223], v[52:55]
	v_mfma_f32_16x16x32_bf16 v[48:51], v[176:179], v[220:223], v[48:51]
	v_mfma_f32_16x16x32_bf16 v[36:39], v[168:171], v[228:231], v[36:39]
	v_mfma_f32_16x16x32_bf16 v[32:35], v[176:179], v[228:231], v[32:35]
	v_mfma_f32_16x16x32_bf16 v[20:23], v[168:171], v[236:239], v[20:23]
	v_mfma_f32_16x16x32_bf16 v[16:19], v[176:179], v[236:239], v[16:19]
	v_mfma_f32_16x16x32_bf16 v[4:7], v[168:171], v[244:247], v[4:7]
	v_mfma_f32_16x16x32_bf16 v[0:3], v[176:179], v[244:247], v[0:3]
	s_barrier
	s_add_i32 s90, s90, 2
	s_add_u32 s84, s84, 0x100
	s_addc_u32 s85, s85, 0
	s_add_u32 s75, s75, 0x100
	s_addc_u32 s77, s77, 0
	s_cmp_gt_u32 s90, 13
	s_cbranch_scc0 .LBB0_232
	s_and_b64 vcc, exec, s[72:73]
	s_cbranch_vccz .LBB0_235
	s_barrier

.LBB0_310:
	s_add_i32 s42, s0, 2
	s_add_u32 s66, s84, 0x80
	s_addc_u32 s86, s85, 0
	s_add_i32 s97, 0, 0x10000
	s_cmp_eq_u32 s88, s0
	s_cselect_b32 s87, s81, s86
	s_cselect_b32 s86, s80, s66
	s_cselect_b32 vcc_hi, s83, s27
	s_cselect_b32 vcc_lo, s82, s26
	s_add_i32 s0, 0, 0x14000
	v_add_u32_e32 v152, s97, v161
	v_add_u32_e32 v172, s0, v161
	ds_read_b128 v[132:135], v152
	ds_read_b128 v[136:139], v152 offset:1024
	ds_read_b128 v[148:151], v152 offset:2048
	ds_read_b128 v[152:155], v152 offset:3072
	ds_read_b128 v[156:159], v172
	ds_read_b128 v[164:167], v172 offset:1024
	ds_read_b128 v[168:171], v172 offset:2048
	ds_read_b128 v[172:175], v172 offset:3072
	v_lshl_add_u64 v[180:181], s[84:85], 0, v[144:145]
	s_add_i32 m0, s23, 0xc000
	ds_read_b128 v[176:179], v163
	ds_read_b128 v[188:191], v163 offset:1024
	ds_read_b128 v[220:223], v163 offset:2048
	ds_read_b128 v[224:227], v163 offset:3072
	ds_read_b128 v[228:231], v163 offset:4096
	ds_read_b128 v[232:235], v163 offset:5120
	ds_read_b128 v[236:239], v163 offset:6144
	ds_read_b128 v[240:243], v163 offset:7168
	global_load_lds_dwordx4 v[180:181], off
	v_lshl_add_u64 v[180:181], s[84:85], 0, v[146:147]
	s_add_i32 m0, s23, 0xe000
	s_nop 0
	global_load_lds_dwordx4 v[180:181], off
	s_waitcnt vmcnt(8)
	s_waitcnt lgkmcnt(0)
	s_barrier
	s_waitcnt lgkmcnt(0)
	v_mfma_f32_16x16x32_bf16 v[128:131], v[132:135], v[176:179], v[128:131]
	v_mfma_f32_16x16x32_bf16 v[124:127], v[148:151], v[176:179], v[124:127]
	v_mfma_f32_16x16x32_bf16 v[112:115], v[132:135], v[220:223], v[112:115]
	v_mfma_f32_16x16x32_bf16 v[108:111], v[148:151], v[220:223], v[108:111]
	v_mfma_f32_16x16x32_bf16 v[92:95], v[132:135], v[228:231], v[92:95]
	v_mfma_f32_16x16x32_bf16 v[88:91], v[148:151], v[228:231], v[88:91]
	v_mfma_f32_16x16x32_bf16 v[76:79], v[132:135], v[236:239], v[76:79]
	v_mfma_f32_16x16x32_bf16 v[72:75], v[148:151], v[236:239], v[72:75]
	v_mfma_f32_16x16x32_bf16 v[128:131], v[136:139], v[188:191], v[128:131]
	v_mfma_f32_16x16x32_bf16 v[124:127], v[152:155], v[188:191], v[124:127]
	v_mfma_f32_16x16x32_bf16 v[112:115], v[136:139], v[224:227], v[112:115]
	v_mfma_f32_16x16x32_bf16 v[108:111], v[152:155], v[224:227], v[108:111]
	v_mfma_f32_16x16x32_bf16 v[92:95], v[136:139], v[232:235], v[92:95]
	v_mfma_f32_16x16x32_bf16 v[88:91], v[152:155], v[232:235], v[88:91]
	v_mfma_f32_16x16x32_bf16 v[76:79], v[136:139], v[240:243], v[76:79]
	v_mfma_f32_16x16x32_bf16 v[72:75], v[152:155], v[240:243], v[72:75]
	v_mfma_f32_16x16x32_bf16 v[120:123], v[156:159], v[176:179], v[120:123]
	v_mfma_f32_16x16x32_bf16 v[116:119], v[168:171], v[176:179], v[116:119]
	v_mfma_f32_16x16x32_bf16 v[104:107], v[156:159], v[220:223], v[104:107]
	v_mfma_f32_16x16x32_bf16 v[100:103], v[168:171], v[220:223], v[100:103]
	v_mfma_f32_16x16x32_bf16 v[84:87], v[156:159], v[228:231], v[84:87]
	v_mfma_f32_16x16x32_bf16 v[80:83], v[168:171], v[228:231], v[80:83]
	v_mfma_f32_16x16x32_bf16 v[68:71], v[156:159], v[236:239], v[68:71]
	v_mfma_f32_16x16x32_bf16 v[64:67], v[168:171], v[236:239], v[64:67]
	v_mfma_f32_16x16x32_bf16 v[120:123], v[164:167], v[188:191], v[120:123]
	v_mfma_f32_16x16x32_bf16 v[116:119], v[172:175], v[188:191], v[116:119]
	v_mfma_f32_16x16x32_bf16 v[104:107], v[164:167], v[224:227], v[104:107]
	v_mfma_f32_16x16x32_bf16 v[100:103], v[172:175], v[224:227], v[100:103]
	v_mfma_f32_16x16x32_bf16 v[84:87], v[164:167], v[232:235], v[84:87]
	v_mfma_f32_16x16x32_bf16 v[80:83], v[172:175], v[232:235], v[80:83]
	v_mfma_f32_16x16x32_bf16 v[68:71], v[164:167], v[240:243], v[68:71]
	v_mfma_f32_16x16x32_bf16 v[64:67], v[172:175], v[240:243], v[64:67]
	s_barrier
	s_add_i32 s66, s97, s10
	v_lshl_add_u64 v[180:181], vcc, 0, v[98:99]
	s_mov_b32 m0, s66
	ds_read_b128 v[176:179], v163 offset:16384
	ds_read_b128 v[188:191], v163 offset:17408
	ds_read_b128 v[220:223], v163 offset:18432
	ds_read_b128 v[224:227], v163 offset:19456
	ds_read_b128 v[228:231], v163 offset:20480
	ds_read_b128 v[232:235], v163 offset:21504
	ds_read_b128 v[236:239], v163 offset:22528
	ds_read_b128 v[240:243], v163 offset:23552
	global_load_lds_dwordx4 v[180:181], off
	s_add_i32 m0, s66, 0x2000
	v_lshl_add_u64 v[192:193], vcc, 0, v[142:143]
	s_add_u32 vcc_lo, vcc_lo, s72
	s_addc_u32 vcc_hi, vcc_hi, 0
	s_add_i32 s0, s0, s10
	global_load_lds_dwordx4 v[192:193], off
	v_lshl_add_u64 v[244:245], vcc, 0, v[98:99]
	s_mov_b32 m0, s0
	v_lshl_add_u64 v[246:247], vcc, 0, v[142:143]
	global_load_lds_dwordx4 v[244:245], off
	s_add_i32 m0, s0, 0x2000
	v_lshl_add_u64 v[248:249], s[86:87], 0, v[96:97]
	global_load_lds_dwordx4 v[246:247], off
	s_mov_b32 m0, s23
	v_lshl_add_u64 v[250:251], s[86:87], 0, v[140:141]
	global_load_lds_dwordx4 v[248:249], off
	s_mov_b32 m0, s33
	s_nop 0
	global_load_lds_dwordx4 v[250:251], off
	s_waitcnt vmcnt(8)
	s_waitcnt lgkmcnt(0)
	s_barrier
	s_waitcnt lgkmcnt(0)
	v_mfma_f32_16x16x32_bf16 v[60:63], v[132:135], v[176:179], v[60:63]
	v_mfma_f32_16x16x32_bf16 v[56:59], v[148:151], v[176:179], v[56:59]
	v_mfma_f32_16x16x32_bf16 v[44:47], v[132:135], v[220:223], v[44:47]
	v_mfma_f32_16x16x32_bf16 v[40:43], v[148:151], v[220:223], v[40:43]
	v_mfma_f32_16x16x32_bf16 v[28:31], v[132:135], v[228:231], v[28:31]
	v_mfma_f32_16x16x32_bf16 v[24:27], v[148:151], v[228:231], v[24:27]
	v_mfma_f32_16x16x32_bf16 v[12:15], v[132:135], v[236:239], v[12:15]
	v_mfma_f32_16x16x32_bf16 v[8:11], v[148:151], v[236:239], v[8:11]
	v_mfma_f32_16x16x32_bf16 v[60:63], v[136:139], v[188:191], v[60:63]
	v_mfma_f32_16x16x32_bf16 v[56:59], v[152:155], v[188:191], v[56:59]
	v_mfma_f32_16x16x32_bf16 v[44:47], v[136:139], v[224:227], v[44:47]
	v_mfma_f32_16x16x32_bf16 v[40:43], v[152:155], v[224:227], v[40:43]
	v_mfma_f32_16x16x32_bf16 v[28:31], v[136:139], v[232:235], v[28:31]
	v_mfma_f32_16x16x32_bf16 v[24:27], v[152:155], v[232:235], v[24:27]
	v_mfma_f32_16x16x32_bf16 v[12:15], v[136:139], v[240:243], v[12:15]
	v_mfma_f32_16x16x32_bf16 v[8:11], v[152:155], v[240:243], v[8:11]
	v_mfma_f32_16x16x32_bf16 v[52:55], v[156:159], v[176:179], v[52:55]
	v_mfma_f32_16x16x32_bf16 v[48:51], v[168:171], v[176:179], v[48:51]
	v_mfma_f32_16x16x32_bf16 v[36:39], v[156:159], v[220:223], v[36:39]
	v_mfma_f32_16x16x32_bf16 v[32:35], v[168:171], v[220:223], v[32:35]
	v_mfma_f32_16x16x32_bf16 v[20:23], v[156:159], v[228:231], v[20:23]
	v_mfma_f32_16x16x32_bf16 v[16:19], v[168:171], v[228:231], v[16:19]
	v_mfma_f32_16x16x32_bf16 v[4:7], v[156:159], v[236:239], v[4:7]
	v_mfma_f32_16x16x32_bf16 v[0:3], v[168:171], v[236:239], v[0:3]
	v_mfma_f32_16x16x32_bf16 v[52:55], v[164:167], v[188:191], v[52:55]
	v_mfma_f32_16x16x32_bf16 v[48:51], v[172:175], v[188:191], v[48:51]
	v_mfma_f32_16x16x32_bf16 v[36:39], v[164:167], v[224:227], v[36:39]
	v_mfma_f32_16x16x32_bf16 v[32:35], v[172:175], v[224:227], v[32:35]
	v_mfma_f32_16x16x32_bf16 v[20:23], v[164:167], v[232:235], v[20:23]
	v_mfma_f32_16x16x32_bf16 v[16:19], v[172:175], v[232:235], v[16:19]
	v_mfma_f32_16x16x32_bf16 v[4:7], v[164:167], v[240:243], v[4:7]
	v_mfma_f32_16x16x32_bf16 v[0:3], v[172:175], v[240:243], v[0:3]
	s_barrier
	s_add_i32 s0, 0, 0x18000
	s_add_i32 s66, 0, 0x1c000
	v_add_u32_e32 v152, s0, v161
	v_add_u32_e32 v172, s66, v161
	ds_read_b128 v[132:135], v152
	ds_read_b128 v[136:139], v152 offset:1024
	ds_read_b128 v[148:151], v152 offset:2048
	ds_read_b128 v[152:155], v152 offset:3072
	ds_read_b128 v[156:159], v172
	ds_read_b128 v[164:167], v172 offset:1024
	ds_read_b128 v[168:171], v172 offset:2048
	ds_read_b128 v[172:175], v172 offset:3072
	s_add_u32 s86, s86, s72
	s_addc_u32 s87, s87, 0
	s_mov_b32 m0, s43
	v_lshl_add_u64 v[252:253], s[86:87], 0, v[96:97]
	ds_read_b128 v[176:179], v163 offset:32768
	ds_read_b128 v[188:191], v163 offset:33792
	ds_read_b128 v[220:223], v163 offset:34816
	ds_read_b128 v[224:227], v163 offset:35840
	ds_read_b128 v[228:231], v163 offset:36864
	ds_read_b128 v[232:235], v163 offset:37888
	ds_read_b128 v[236:239], v163 offset:38912
	ds_read_b128 v[240:243], v163 offset:39936
	global_load_lds_dwordx4 v[252:253], off
	v_lshl_add_u64 v[252:253], s[86:87], 0, v[140:141]
	s_mov_b32 m0, s44
	s_nop 0
	global_load_lds_dwordx4 v[252:253], off
	s_waitcnt vmcnt(8)
	s_waitcnt lgkmcnt(0)
	s_barrier
	s_waitcnt lgkmcnt(0)
	v_mfma_f32_16x16x32_bf16 v[128:131], v[132:135], v[176:179], v[128:131]
	v_mfma_f32_16x16x32_bf16 v[124:127], v[148:151], v[176:179], v[124:127]
	v_mfma_f32_16x16x32_bf16 v[112:115], v[132:135], v[220:223], v[112:115]
	v_mfma_f32_16x16x32_bf16 v[108:111], v[148:151], v[220:223], v[108:111]
	v_mfma_f32_16x16x32_bf16 v[92:95], v[132:135], v[228:231], v[92:95]
	v_mfma_f32_16x16x32_bf16 v[88:91], v[148:151], v[228:231], v[88:91]
	v_mfma_f32_16x16x32_bf16 v[76:79], v[132:135], v[236:239], v[76:79]
	v_mfma_f32_16x16x32_bf16 v[72:75], v[148:151], v[236:239], v[72:75]
	v_mfma_f32_16x16x32_bf16 v[128:131], v[136:139], v[188:191], v[128:131]
	v_mfma_f32_16x16x32_bf16 v[124:127], v[152:155], v[188:191], v[124:127]
	v_mfma_f32_16x16x32_bf16 v[112:115], v[136:139], v[224:227], v[112:115]
	v_mfma_f32_16x16x32_bf16 v[108:111], v[152:155], v[224:227], v[108:111]
	v_mfma_f32_16x16x32_bf16 v[92:95], v[136:139], v[232:235], v[92:95]
	v_mfma_f32_16x16x32_bf16 v[88:91], v[152:155], v[232:235], v[88:91]
	v_mfma_f32_16x16x32_bf16 v[76:79], v[136:139], v[240:243], v[76:79]
	v_mfma_f32_16x16x32_bf16 v[72:75], v[152:155], v[240:243], v[72:75]
	v_mfma_f32_16x16x32_bf16 v[120:123], v[156:159], v[176:179], v[120:123]
	v_mfma_f32_16x16x32_bf16 v[116:119], v[168:171], v[176:179], v[116:119]
	v_mfma_f32_16x16x32_bf16 v[104:107], v[156:159], v[220:223], v[104:107]
	v_mfma_f32_16x16x32_bf16 v[100:103], v[168:171], v[220:223], v[100:103]
	v_mfma_f32_16x16x32_bf16 v[84:87], v[156:159], v[228:231], v[84:87]
	v_mfma_f32_16x16x32_bf16 v[80:83], v[168:171], v[228:231], v[80:83]
	v_mfma_f32_16x16x32_bf16 v[68:71], v[156:159], v[236:239], v[68:71]
	v_mfma_f32_16x16x32_bf16 v[64:67], v[168:171], v[236:239], v[64:67]
	v_mfma_f32_16x16x32_bf16 v[120:123], v[164:167], v[188:191], v[120:123]
	v_mfma_f32_16x16x32_bf16 v[116:119], v[172:175], v[188:191], v[116:119]
	v_mfma_f32_16x16x32_bf16 v[104:107], v[164:167], v[224:227], v[104:107]
	v_mfma_f32_16x16x32_bf16 v[100:103], v[172:175], v[224:227], v[100:103]
	v_mfma_f32_16x16x32_bf16 v[84:87], v[164:167], v[232:235], v[84:87]
	v_mfma_f32_16x16x32_bf16 v[80:83], v[172:175], v[232:235], v[80:83]
	v_mfma_f32_16x16x32_bf16 v[68:71], v[164:167], v[240:243], v[68:71]
	v_mfma_f32_16x16x32_bf16 v[64:67], v[172:175], v[240:243], v[64:67]
	s_barrier
	s_add_i32 s0, s0, s10
	v_lshl_add_u64 v[180:181], v[180:181], 0, s[58:59]
	s_mov_b32 m0, s0
	ds_read_b128 v[176:179], v163 offset:49152
	ds_read_b128 v[188:191], v163 offset:50176
	ds_read_b128 v[220:223], v163 offset:51200
	ds_read_b128 v[224:227], v163 offset:52224
	ds_read_b128 v[228:231], v163 offset:53248
	ds_read_b128 v[232:235], v163 offset:54272
	ds_read_b128 v[236:239], v163 offset:55296
	ds_read_b128 v[240:243], v163 offset:56320
	global_load_lds_dwordx4 v[180:181], off
	v_lshl_add_u64 v[180:181], v[192:193], 0, s[58:59]
	s_add_i32 m0, s0, 0x2000
	s_add_i32 s0, s66, s10
	global_load_lds_dwordx4 v[180:181], off
	v_lshl_add_u64 v[180:181], v[244:245], 0, s[58:59]
	s_mov_b32 m0, s0
	s_nop 0
	global_load_lds_dwordx4 v[180:181], off
	v_lshl_add_u64 v[180:181], v[246:247], 0, s[58:59]
	s_add_i32 m0, s0, 0x2000
	s_nop 0
	global_load_lds_dwordx4 v[180:181], off
	v_lshl_add_u64 v[180:181], v[248:249], 0, s[58:59]
	s_mov_b32 m0, s47
	s_nop 0
	global_load_lds_dwordx4 v[180:181], off
	v_lshl_add_u64 v[180:181], v[250:251], 0, s[58:59]
	s_mov_b32 m0, s56
	s_nop 0
	global_load_lds_dwordx4 v[180:181], off
	s_waitcnt vmcnt(8)
	s_waitcnt lgkmcnt(0)
	s_barrier
	s_waitcnt lgkmcnt(0)
	v_mfma_f32_16x16x32_bf16 v[60:63], v[132:135], v[176:179], v[60:63]
	v_mfma_f32_16x16x32_bf16 v[56:59], v[148:151], v[176:179], v[56:59]
	v_mfma_f32_16x16x32_bf16 v[44:47], v[132:135], v[220:223], v[44:47]
	v_mfma_f32_16x16x32_bf16 v[40:43], v[148:151], v[220:223], v[40:43]
	v_mfma_f32_16x16x32_bf16 v[28:31], v[132:135], v[228:231], v[28:31]
	v_mfma_f32_16x16x32_bf16 v[24:27], v[148:151], v[228:231], v[24:27]
	v_mfma_f32_16x16x32_bf16 v[12:15], v[132:135], v[236:239], v[12:15]
	v_mfma_f32_16x16x32_bf16 v[8:11], v[148:151], v[236:239], v[8:11]
	v_mfma_f32_16x16x32_bf16 v[60:63], v[136:139], v[188:191], v[60:63]
	v_mfma_f32_16x16x32_bf16 v[56:59], v[152:155], v[188:191], v[56:59]
	v_mfma_f32_16x16x32_bf16 v[44:47], v[136:139], v[224:227], v[44:47]
	v_mfma_f32_16x16x32_bf16 v[40:43], v[152:155], v[224:227], v[40:43]
	v_mfma_f32_16x16x32_bf16 v[28:31], v[136:139], v[232:235], v[28:31]
	v_mfma_f32_16x16x32_bf16 v[24:27], v[152:155], v[232:235], v[24:27]
	v_mfma_f32_16x16x32_bf16 v[12:15], v[136:139], v[240:243], v[12:15]
	v_mfma_f32_16x16x32_bf16 v[8:11], v[152:155], v[240:243], v[8:11]
	v_mfma_f32_16x16x32_bf16 v[52:55], v[156:159], v[176:179], v[52:55]
	v_mfma_f32_16x16x32_bf16 v[48:51], v[168:171], v[176:179], v[48:51]
	v_mfma_f32_16x16x32_bf16 v[36:39], v[156:159], v[220:223], v[36:39]
	v_mfma_f32_16x16x32_bf16 v[32:35], v[168:171], v[220:223], v[32:35]
	v_mfma_f32_16x16x32_bf16 v[20:23], v[156:159], v[228:231], v[20:23]
	v_mfma_f32_16x16x32_bf16 v[16:19], v[168:171], v[228:231], v[16:19]
	v_mfma_f32_16x16x32_bf16 v[4:7], v[156:159], v[236:239], v[4:7]
	v_mfma_f32_16x16x32_bf16 v[0:3], v[168:171], v[236:239], v[0:3]
	v_mfma_f32_16x16x32_bf16 v[52:55], v[164:167], v[188:191], v[52:55]
	v_mfma_f32_16x16x32_bf16 v[48:51], v[172:175], v[188:191], v[48:51]
	v_mfma_f32_16x16x32_bf16 v[36:39], v[164:167], v[224:227], v[36:39]
	v_mfma_f32_16x16x32_bf16 v[32:35], v[172:175], v[224:227], v[32:35]
	v_mfma_f32_16x16x32_bf16 v[20:23], v[164:167], v[232:235], v[20:23]
	v_mfma_f32_16x16x32_bf16 v[16:19], v[172:175], v[232:235], v[16:19]
	v_mfma_f32_16x16x32_bf16 v[4:7], v[164:167], v[240:243], v[4:7]
	v_mfma_f32_16x16x32_bf16 v[0:3], v[172:175], v[240:243], v[0:3]
	s_barrier
	s_add_u32 s84, s84, 0x100
	s_addc_u32 s85, s85, 0
	s_add_u32 s26, s26, 0x100
	s_addc_u32 s27, s27, 0
	s_cmp_ge_u32 s42, s67
	s_mov_b32 s0, s42
	s_cbranch_scc0 .LBB0_310
	s_and_b64 vcc, exec, s[78:79]
	s_cbranch_vccz .LBB0_313
	s_barrier

.LBB0_346:
	s_add_u32 s80, s78, 0xfffc0080
	s_addc_u32 s81, s79, -1
	s_add_i32 s85, 0, 0x10000
	s_cmp_eq_u32 s84, 12
	s_cselect_b32 s83, s27, s81
	s_cselect_b32 s82, s42, s80
	s_cselect_b32 s81, s56, s71
	s_cselect_b32 s80, s57, s69
	s_add_i32 s88, 0, 0x14000
	v_add_u32_e32 v160, s85, v145
	v_add_u32_e32 v176, s88, v145
	ds_read_b128 v[140:143], v160
	ds_read_b128 v[152:155], v160 offset:1024
	ds_read_b128 v[156:159], v160 offset:2048
	ds_read_b128 v[160:163], v160 offset:3072
	ds_read_b128 v[164:167], v176
	ds_read_b128 v[168:171], v176 offset:1024
	ds_read_b128 v[172:175], v176 offset:2048
	ds_read_b128 v[176:179], v176 offset:3072
	v_lshl_add_u64 v[180:181], s[78:79], 0, v[136:137]
	s_add_i32 m0, s11, 0xc000
	ds_read_b128 v[188:191], v151
	ds_read_b128 v[220:223], v151 offset:1024
	ds_read_b128 v[224:227], v151 offset:2048
	ds_read_b128 v[228:231], v151 offset:3072
	ds_read_b128 v[232:235], v151 offset:4096
	ds_read_b128 v[236:239], v151 offset:5120
	ds_read_b128 v[240:243], v151 offset:6144
	ds_read_b128 v[244:247], v151 offset:7168
	global_load_lds_dwordx4 v[180:181], off
	v_lshl_add_u64 v[180:181], s[78:79], 0, v[138:139]
	s_add_i32 m0, s11, 0xe000
	s_nop 0
	global_load_lds_dwordx4 v[180:181], off
	s_waitcnt vmcnt(8)
	s_waitcnt lgkmcnt(0)
	s_barrier
	s_waitcnt lgkmcnt(0)
	v_mfma_f32_16x16x32_bf16 v[128:131], v[140:143], v[188:191], v[128:131]
	v_mfma_f32_16x16x32_bf16 v[120:123], v[156:159], v[188:191], v[120:123]
	v_mfma_f32_16x16x32_bf16 v[112:115], v[140:143], v[224:227], v[112:115]
	v_mfma_f32_16x16x32_bf16 v[104:107], v[156:159], v[224:227], v[104:107]
	v_mfma_f32_16x16x32_bf16 v[92:95], v[140:143], v[232:235], v[92:95]
	v_mfma_f32_16x16x32_bf16 v[84:87], v[156:159], v[232:235], v[84:87]
	v_mfma_f32_16x16x32_bf16 v[76:79], v[140:143], v[240:243], v[76:79]
	v_mfma_f32_16x16x32_bf16 v[68:71], v[156:159], v[240:243], v[68:71]
	v_mfma_f32_16x16x32_bf16 v[128:131], v[152:155], v[220:223], v[128:131]
	v_mfma_f32_16x16x32_bf16 v[120:123], v[160:163], v[220:223], v[120:123]
	v_mfma_f32_16x16x32_bf16 v[112:115], v[152:155], v[228:231], v[112:115]
	v_mfma_f32_16x16x32_bf16 v[104:107], v[160:163], v[228:231], v[104:107]
	v_mfma_f32_16x16x32_bf16 v[92:95], v[152:155], v[236:239], v[92:95]
	v_mfma_f32_16x16x32_bf16 v[84:87], v[160:163], v[236:239], v[84:87]
	v_mfma_f32_16x16x32_bf16 v[76:79], v[152:155], v[244:247], v[76:79]
	v_mfma_f32_16x16x32_bf16 v[68:71], v[160:163], v[244:247], v[68:71]
	v_mfma_f32_16x16x32_bf16 v[124:127], v[164:167], v[188:191], v[124:127]
	v_mfma_f32_16x16x32_bf16 v[116:119], v[172:175], v[188:191], v[116:119]
	v_mfma_f32_16x16x32_bf16 v[108:111], v[164:167], v[224:227], v[108:111]
	v_mfma_f32_16x16x32_bf16 v[100:103], v[172:175], v[224:227], v[100:103]
	v_mfma_f32_16x16x32_bf16 v[88:91], v[164:167], v[232:235], v[88:91]
	v_mfma_f32_16x16x32_bf16 v[80:83], v[172:175], v[232:235], v[80:83]
	v_mfma_f32_16x16x32_bf16 v[72:75], v[164:167], v[240:243], v[72:75]
	v_mfma_f32_16x16x32_bf16 v[64:67], v[172:175], v[240:243], v[64:67]
	v_mfma_f32_16x16x32_bf16 v[124:127], v[168:171], v[220:223], v[124:127]
	v_mfma_f32_16x16x32_bf16 v[116:119], v[176:179], v[220:223], v[116:119]
	v_mfma_f32_16x16x32_bf16 v[108:111], v[168:171], v[228:231], v[108:111]
	v_mfma_f32_16x16x32_bf16 v[100:103], v[176:179], v[228:231], v[100:103]
	v_mfma_f32_16x16x32_bf16 v[88:91], v[168:171], v[236:239], v[88:91]
	v_mfma_f32_16x16x32_bf16 v[80:83], v[176:179], v[236:239], v[80:83]
	v_mfma_f32_16x16x32_bf16 v[72:75], v[168:171], v[244:247], v[72:75]
	v_mfma_f32_16x16x32_bf16 v[64:67], v[176:179], v[244:247], v[64:67]
	s_barrier
	s_add_i32 s85, s85, s10
	v_lshl_add_u64 v[180:181], s[80:81], 0, v[98:99]
	s_mov_b32 m0, s85
	ds_read_b128 v[188:191], v151 offset:16384
	ds_read_b128 v[220:223], v151 offset:17408
	ds_read_b128 v[224:227], v151 offset:18432
	ds_read_b128 v[228:231], v151 offset:19456
	ds_read_b128 v[232:235], v151 offset:20480
	ds_read_b128 v[236:239], v151 offset:21504
	ds_read_b128 v[240:243], v151 offset:22528
	ds_read_b128 v[244:247], v151 offset:23552
	global_load_lds_dwordx4 v[180:181], off
	s_add_i32 m0, s85, 0x2000
	s_add_u32 s86, s80, 0x40000
	v_lshl_add_u64 v[192:193], s[80:81], 0, v[134:135]
	s_addc_u32 s87, s81, 0
	s_add_i32 s85, s88, s10
	global_load_lds_dwordx4 v[192:193], off
	v_lshl_add_u64 v[248:249], s[86:87], 0, v[98:99]
	s_mov_b32 m0, s85
	v_lshl_add_u64 v[250:251], s[82:83], 0, v[132:133]
	global_load_lds_dwordx4 v[248:249], off
	v_lshl_add_u64 v[248:249], s[86:87], 0, v[134:135]
	s_add_i32 m0, s85, 0x2000
	s_nop 0
	global_load_lds_dwordx4 v[248:249], off
	v_lshl_add_u64 v[248:249], s[82:83], 0, v[96:97]
	s_mov_b32 m0, s11
	s_nop 0
	global_load_lds_dwordx4 v[248:249], off
	s_mov_b32 m0, s20
	s_nop 0
	global_load_lds_dwordx4 v[250:251], off
	s_waitcnt vmcnt(8)
	s_waitcnt lgkmcnt(0)
	s_barrier
	s_waitcnt lgkmcnt(0)
	v_mfma_f32_16x16x32_bf16 v[60:63], v[140:143], v[188:191], v[60:63]
	v_mfma_f32_16x16x32_bf16 v[52:55], v[156:159], v[188:191], v[52:55]
	v_mfma_f32_16x16x32_bf16 v[44:47], v[140:143], v[224:227], v[44:47]
	v_mfma_f32_16x16x32_bf16 v[36:39], v[156:159], v[224:227], v[36:39]
	v_mfma_f32_16x16x32_bf16 v[28:31], v[140:143], v[232:235], v[28:31]
	v_mfma_f32_16x16x32_bf16 v[20:23], v[156:159], v[232:235], v[20:23]
	v_mfma_f32_16x16x32_bf16 v[12:15], v[140:143], v[240:243], v[12:15]
	v_mfma_f32_16x16x32_bf16 v[4:7], v[156:159], v[240:243], v[4:7]
	v_mfma_f32_16x16x32_bf16 v[60:63], v[152:155], v[220:223], v[60:63]
	v_mfma_f32_16x16x32_bf16 v[52:55], v[160:163], v[220:223], v[52:55]
	v_mfma_f32_16x16x32_bf16 v[44:47], v[152:155], v[228:231], v[44:47]
	v_mfma_f32_16x16x32_bf16 v[36:39], v[160:163], v[228:231], v[36:39]
	v_mfma_f32_16x16x32_bf16 v[28:31], v[152:155], v[236:239], v[28:31]
	v_mfma_f32_16x16x32_bf16 v[20:23], v[160:163], v[236:239], v[20:23]
	v_mfma_f32_16x16x32_bf16 v[12:15], v[152:155], v[244:247], v[12:15]
	v_mfma_f32_16x16x32_bf16 v[4:7], v[160:163], v[244:247], v[4:7]
	v_mfma_f32_16x16x32_bf16 v[56:59], v[164:167], v[188:191], v[56:59]
	v_mfma_f32_16x16x32_bf16 v[48:51], v[172:175], v[188:191], v[48:51]
	v_mfma_f32_16x16x32_bf16 v[40:43], v[164:167], v[224:227], v[40:43]
	v_mfma_f32_16x16x32_bf16 v[32:35], v[172:175], v[224:227], v[32:35]
	v_mfma_f32_16x16x32_bf16 v[24:27], v[164:167], v[232:235], v[24:27]
	v_mfma_f32_16x16x32_bf16 v[16:19], v[172:175], v[232:235], v[16:19]
	v_mfma_f32_16x16x32_bf16 v[8:11], v[164:167], v[240:243], v[8:11]
	v_mfma_f32_16x16x32_bf16 v[0:3], v[172:175], v[240:243], v[0:3]
	v_mfma_f32_16x16x32_bf16 v[56:59], v[168:171], v[220:223], v[56:59]
	v_mfma_f32_16x16x32_bf16 v[48:51], v[176:179], v[220:223], v[48:51]
	v_mfma_f32_16x16x32_bf16 v[40:43], v[168:171], v[228:231], v[40:43]
	v_mfma_f32_16x16x32_bf16 v[32:35], v[176:179], v[228:231], v[32:35]
	v_mfma_f32_16x16x32_bf16 v[24:27], v[168:171], v[236:239], v[24:27]
	v_mfma_f32_16x16x32_bf16 v[16:19], v[176:179], v[236:239], v[16:19]
	v_mfma_f32_16x16x32_bf16 v[8:11], v[168:171], v[244:247], v[8:11]
	v_mfma_f32_16x16x32_bf16 v[0:3], v[176:179], v[244:247], v[0:3]
	s_barrier
	s_add_i32 s85, 0, 0x18000
	s_add_i32 s86, 0, 0x1c000
	v_add_u32_e32 v160, s85, v145
	v_add_u32_e32 v176, s86, v145
	ds_read_b128 v[140:143], v160
	ds_read_b128 v[152:155], v160 offset:1024
	ds_read_b128 v[156:159], v160 offset:2048
	ds_read_b128 v[160:163], v160 offset:3072
	ds_read_b128 v[164:167], v176
	ds_read_b128 v[168:171], v176 offset:1024
	ds_read_b128 v[172:175], v176 offset:2048
	ds_read_b128 v[176:179], v176 offset:3072
	s_add_u32 s82, s82, 0x40000
	s_addc_u32 s83, s83, 0
	s_mov_b32 m0, s22
	v_lshl_add_u64 v[252:253], s[82:83], 0, v[96:97]
	ds_read_b128 v[188:191], v151 offset:32768
	ds_read_b128 v[220:223], v151 offset:33792
	ds_read_b128 v[224:227], v151 offset:34816
	ds_read_b128 v[228:231], v151 offset:35840
	ds_read_b128 v[232:235], v151 offset:36864
	ds_read_b128 v[236:239], v151 offset:37888
	ds_read_b128 v[240:243], v151 offset:38912
	ds_read_b128 v[244:247], v151 offset:39936
	global_load_lds_dwordx4 v[252:253], off
	v_lshl_add_u64 v[252:253], s[82:83], 0, v[132:133]
	s_mov_b32 m0, s23
	s_nop 0
	global_load_lds_dwordx4 v[252:253], off
	s_waitcnt vmcnt(8)
	s_waitcnt lgkmcnt(0)
	s_barrier
	s_waitcnt lgkmcnt(0)
	v_mfma_f32_16x16x32_bf16 v[128:131], v[140:143], v[188:191], v[128:131]
	v_mfma_f32_16x16x32_bf16 v[120:123], v[156:159], v[188:191], v[120:123]
	v_mfma_f32_16x16x32_bf16 v[112:115], v[140:143], v[224:227], v[112:115]
	v_mfma_f32_16x16x32_bf16 v[104:107], v[156:159], v[224:227], v[104:107]
	v_mfma_f32_16x16x32_bf16 v[92:95], v[140:143], v[232:235], v[92:95]
	v_mfma_f32_16x16x32_bf16 v[84:87], v[156:159], v[232:235], v[84:87]
	v_mfma_f32_16x16x32_bf16 v[76:79], v[140:143], v[240:243], v[76:79]
	v_mfma_f32_16x16x32_bf16 v[68:71], v[156:159], v[240:243], v[68:71]
	v_mfma_f32_16x16x32_bf16 v[128:131], v[152:155], v[220:223], v[128:131]
	v_mfma_f32_16x16x32_bf16 v[120:123], v[160:163], v[220:223], v[120:123]
	v_mfma_f32_16x16x32_bf16 v[112:115], v[152:155], v[228:231], v[112:115]
	v_mfma_f32_16x16x32_bf16 v[104:107], v[160:163], v[228:231], v[104:107]
	v_mfma_f32_16x16x32_bf16 v[92:95], v[152:155], v[236:239], v[92:95]
	v_mfma_f32_16x16x32_bf16 v[84:87], v[160:163], v[236:239], v[84:87]
	v_mfma_f32_16x16x32_bf16 v[76:79], v[152:155], v[244:247], v[76:79]
	v_mfma_f32_16x16x32_bf16 v[68:71], v[160:163], v[244:247], v[68:71]
	v_mfma_f32_16x16x32_bf16 v[124:127], v[164:167], v[188:191], v[124:127]
	v_mfma_f32_16x16x32_bf16 v[116:119], v[172:175], v[188:191], v[116:119]
	v_mfma_f32_16x16x32_bf16 v[108:111], v[164:167], v[224:227], v[108:111]
	v_mfma_f32_16x16x32_bf16 v[100:103], v[172:175], v[224:227], v[100:103]
	v_mfma_f32_16x16x32_bf16 v[88:91], v[164:167], v[232:235], v[88:91]
	v_mfma_f32_16x16x32_bf16 v[80:83], v[172:175], v[232:235], v[80:83]
	v_mfma_f32_16x16x32_bf16 v[72:75], v[164:167], v[240:243], v[72:75]
	v_mfma_f32_16x16x32_bf16 v[64:67], v[172:175], v[240:243], v[64:67]
	v_mfma_f32_16x16x32_bf16 v[124:127], v[168:171], v[220:223], v[124:127]
	v_mfma_f32_16x16x32_bf16 v[116:119], v[176:179], v[220:223], v[116:119]
	v_mfma_f32_16x16x32_bf16 v[108:111], v[168:171], v[228:231], v[108:111]
	v_mfma_f32_16x16x32_bf16 v[100:103], v[176:179], v[228:231], v[100:103]
	v_mfma_f32_16x16x32_bf16 v[88:91], v[168:171], v[236:239], v[88:91]
	v_mfma_f32_16x16x32_bf16 v[80:83], v[176:179], v[236:239], v[80:83]
	v_mfma_f32_16x16x32_bf16 v[72:75], v[168:171], v[244:247], v[72:75]
	v_mfma_f32_16x16x32_bf16 v[64:67], v[176:179], v[244:247], v[64:67]
	s_barrier
	s_add_i32 s82, s85, s10
	v_lshl_add_u64 v[180:181], v[180:181], 0, s[58:59]
	s_mov_b32 m0, s82
	ds_read_b128 v[188:191], v151 offset:49152
	ds_read_b128 v[220:223], v151 offset:50176
	ds_read_b128 v[224:227], v151 offset:51200
	ds_read_b128 v[228:231], v151 offset:52224
	ds_read_b128 v[232:235], v151 offset:53248
	ds_read_b128 v[236:239], v151 offset:54272
	ds_read_b128 v[240:243], v151 offset:55296
	ds_read_b128 v[244:247], v151 offset:56320
	global_load_lds_dwordx4 v[180:181], off
	s_add_i32 m0, s82, 0x2000
	s_add_u32 s80, s80, 0x40080
	v_lshl_add_u64 v[180:181], v[192:193], 0, s[58:59]
	s_addc_u32 s81, s81, 0
	s_add_i32 s82, s86, s10
	global_load_lds_dwordx4 v[180:181], off
	v_lshl_add_u64 v[180:181], s[80:81], 0, v[98:99]
	s_mov_b32 m0, s82
	s_nop 0
	global_load_lds_dwordx4 v[180:181], off
	v_lshl_add_u64 v[180:181], s[80:81], 0, v[134:135]
	s_add_i32 m0, s82, 0x2000
	s_nop 0
	global_load_lds_dwordx4 v[180:181], off
	v_lshl_add_u64 v[180:181], v[248:249], 0, s[58:59]
	s_mov_b32 m0, s33
	s_nop 0
	global_load_lds_dwordx4 v[180:181], off
	v_lshl_add_u64 v[180:181], v[250:251], 0, s[58:59]
	s_mov_b32 m0, s43
	s_nop 0
	global_load_lds_dwordx4 v[180:181], off
	s_waitcnt vmcnt(8)
	s_waitcnt lgkmcnt(0)
	s_barrier
	s_waitcnt lgkmcnt(0)
	v_mfma_f32_16x16x32_bf16 v[60:63], v[140:143], v[188:191], v[60:63]
	v_mfma_f32_16x16x32_bf16 v[52:55], v[156:159], v[188:191], v[52:55]
	v_mfma_f32_16x16x32_bf16 v[44:47], v[140:143], v[224:227], v[44:47]
	v_mfma_f32_16x16x32_bf16 v[36:39], v[156:159], v[224:227], v[36:39]
	v_mfma_f32_16x16x32_bf16 v[28:31], v[140:143], v[232:235], v[28:31]
	v_mfma_f32_16x16x32_bf16 v[20:23], v[156:159], v[232:235], v[20:23]
	v_mfma_f32_16x16x32_bf16 v[12:15], v[140:143], v[240:243], v[12:15]
	v_mfma_f32_16x16x32_bf16 v[4:7], v[156:159], v[240:243], v[4:7]
	v_mfma_f32_16x16x32_bf16 v[60:63], v[152:155], v[220:223], v[60:63]
	v_mfma_f32_16x16x32_bf16 v[52:55], v[160:163], v[220:223], v[52:55]
	v_mfma_f32_16x16x32_bf16 v[44:47], v[152:155], v[228:231], v[44:47]
	v_mfma_f32_16x16x32_bf16 v[36:39], v[160:163], v[228:231], v[36:39]
	v_mfma_f32_16x16x32_bf16 v[28:31], v[152:155], v[236:239], v[28:31]
	v_mfma_f32_16x16x32_bf16 v[20:23], v[160:163], v[236:239], v[20:23]
	v_mfma_f32_16x16x32_bf16 v[12:15], v[152:155], v[244:247], v[12:15]
	v_mfma_f32_16x16x32_bf16 v[4:7], v[160:163], v[244:247], v[4:7]
	v_mfma_f32_16x16x32_bf16 v[56:59], v[164:167], v[188:191], v[56:59]
	v_mfma_f32_16x16x32_bf16 v[48:51], v[172:175], v[188:191], v[48:51]
	v_mfma_f32_16x16x32_bf16 v[40:43], v[164:167], v[224:227], v[40:43]
	v_mfma_f32_16x16x32_bf16 v[32:35], v[172:175], v[224:227], v[32:35]
	v_mfma_f32_16x16x32_bf16 v[24:27], v[164:167], v[232:235], v[24:27]
	v_mfma_f32_16x16x32_bf16 v[16:19], v[172:175], v[232:235], v[16:19]
	v_mfma_f32_16x16x32_bf16 v[8:11], v[164:167], v[240:243], v[8:11]
	v_mfma_f32_16x16x32_bf16 v[0:3], v[172:175], v[240:243], v[0:3]
	v_mfma_f32_16x16x32_bf16 v[56:59], v[168:171], v[220:223], v[56:59]
	v_mfma_f32_16x16x32_bf16 v[48:51], v[176:179], v[220:223], v[48:51]
	v_mfma_f32_16x16x32_bf16 v[40:43], v[168:171], v[228:231], v[40:43]
	v_mfma_f32_16x16x32_bf16 v[32:35], v[176:179], v[228:231], v[32:35]
	v_mfma_f32_16x16x32_bf16 v[24:27], v[168:171], v[236:239], v[24:27]
	v_mfma_f32_16x16x32_bf16 v[16:19], v[176:179], v[236:239], v[16:19]
	v_mfma_f32_16x16x32_bf16 v[8:11], v[168:171], v[244:247], v[8:11]
	v_mfma_f32_16x16x32_bf16 v[0:3], v[176:179], v[244:247], v[0:3]
	s_barrier
	s_add_i32 s84, s84, 2
	s_add_u32 s78, s78, 0x100
	s_addc_u32 s79, s79, 0
	s_add_u32 s69, s69, 0x100
	s_addc_u32 s71, s71, 0
	s_cmp_gt_u32 s84, 13
	s_cbranch_scc0 .LBB0_346
	s_and_b64 vcc, exec, s[66:67]
	s_cbranch_vccz .LBB0_349
	s_barrier
